# lora GEMM: decay tiles pair with gate tiles on 132 workgroups, a_lr tiles run alone
# speedup vs baseline: 1.0144x; 1.0059x over previous
.LBB0_763:
	s_cmpk_lt_i32 s2, 0xfe
	s_cselect_b64 s[0:1], -1, 0
	s_cmpk_gt_i32 s2, 0xfd
	v_readfirstlane_b32 s18, v166
	s_cbranch_scc1 .LBB0_769
	s_cmp_lt_u32 s2, 0x84
	s_cbranch_scc1 .Lp3_a
	s_add_i32 s3, s2, 0xffffff7c
	s_mov_b32 s4, 4
	s_branch .Lp3_j
.Lp3_a:
	s_mov_b32 s3, s2
	s_mov_b32 s4, 0
